# v68 + attention: the wait after the last QK^T MFMA filled with scalar/LDS-DMA work taken from the serial tail of the mid section (s_nop 2 -> 3 address ops; s_nop 5 -> the first DMA group)
# baseline (speedup 1.0000x reference)
.LBB0_1604:
	v_add_u32_e32 v0, s22, v244
	ds_read_b64_tr_b16 v[208:209], v0 offset:24576
	ds_read_b64_tr_b16 v[210:211], v0 offset:25088
	s_waitcnt lgkmcnt(9)
	v_mfma_f32_32x32x16_bf16 v[112:127], v[204:207], v[172:175], 0
	v_add_f32_e32 v2, v87, v88
	v_cvt_pk_bf16_f32 v156, v96, v97
	v_cvt_pk_bf16_f32 v157, v98, v99
	ds_read_b64_tr_b16 v[204:205], v0 offset:28672
	ds_read_b64_tr_b16 v[206:207], v0 offset:29184
	v_add_f32_e32 v2, v89, v2
	v_cvt_pk_bf16_f32 v158, v100, v101
	v_cvt_pk_bf16_f32 v159, v102, v103
	s_waitcnt lgkmcnt(10)
	v_mfma_f32_32x32x16_bf16 v[128:143], v[200:203], v[172:175], 0
	ds_read_b64_tr_b16 v[10:11], v0 offset:25600
	ds_read_b64_tr_b16 v[12:13], v0 offset:26112
	s_waitcnt lgkmcnt(11)
	v_mfma_f32_32x32x16_bf16 v[112:127], v[196:199], v[168:171], v[112:127]
	v_add_f32_e32 v2, v90, v2
	v_cvt_pk_bf16_f32 v152, v104, v105
	v_cvt_pk_bf16_f32 v153, v106, v107
	ds_read_b64_tr_b16 v[6:7], v0 offset:29696
	ds_read_b64_tr_b16 v[8:9], v0 offset:30208
	v_add_f32_e32 v14, v91, v2
	v_cvt_pk_bf16_f32 v154, v108, v109
	v_cvt_pk_bf16_f32 v155, v110, v111
	s_waitcnt lgkmcnt(12)
	v_mfma_f32_32x32x16_bf16 v[128:143], v[192:195], v[168:171], v[128:143]
	ds_read_b64_tr_b16 v[2:3], v0 offset:26624
	ds_read_b64_tr_b16 v[4:5], v0 offset:27136
	s_waitcnt lgkmcnt(13)
	v_mfma_f32_32x32x16_bf16 v[112:127], v[188:191], v[164:167], v[112:127]
	v_add_f32_e32 v14, v92, v14
	v_cvt_pk_bf16_f32 v148, v80, v81
	v_cvt_pk_bf16_f32 v149, v82, v83
	ds_read_b64_tr_b16 v[196:197], v0 offset:30720
	ds_read_b64_tr_b16 v[198:199], v0 offset:31232
	v_add_f32_e32 v14, v93, v14
	v_cvt_pk_bf16_f32 v150, v84, v85
	v_cvt_pk_bf16_f32 v151, v86, v87
	s_waitcnt lgkmcnt(14)
	v_mfma_f32_32x32x16_bf16 v[128:143], v[184:187], v[164:167], v[128:143]
	ds_read_b64_tr_b16 v[192:193], v0 offset:27648
	ds_read_b64_tr_b16 v[194:195], v0 offset:28160
	s_waitcnt lgkmcnt(14)
	v_mfma_f32_32x32x16_bf16 v[112:127], v[180:183], v[160:163], v[112:127]
	v_add_f32_e32 v14, v94, v14
	v_cvt_pk_bf16_f32 v144, v88, v89
	v_cvt_pk_bf16_f32 v145, v90, v91
	ds_read_b64_tr_b16 v[188:189], v0 offset:31744
	ds_read_b64_tr_b16 v[190:191], v0 offset:32256
	v_add_f32_e32 v96, v95, v14
	v_cvt_pk_bf16_f32 v146, v92, v93
	v_cvt_pk_bf16_f32 v147, v94, v95
	v_mfma_f32_32x32x16_bf16 v[128:143], v[176:179], v[160:163], v[128:143]
	s_add_u32 s30, s16, s10
	s_addc_u32 s31, s17, s11
	s_add_u32 s22, s30, 0x80000
	v_add_f32_e64 v80, v112, -v228
	v_add_f32_e64 v81, v113, -v228
	v_pk_add_f32 v[98:99], v[114:115], v[228:229] op_sel_hi:[1,0] neg_lo:[0,1] neg_hi:[0,1]
	v_pk_add_f32 v[100:101], v[116:117], v[228:229] op_sel_hi:[1,0] neg_lo:[0,1] neg_hi:[0,1]
	v_pk_add_f32 v[102:103], v[118:119], v[228:229] op_sel_hi:[1,0] neg_lo:[0,1] neg_hi:[0,1]
	v_pk_add_f32 v[104:105], v[120:121], v[228:229] op_sel_hi:[1,0] neg_lo:[0,1] neg_hi:[0,1]
	v_pk_add_f32 v[106:107], v[122:123], v[228:229] op_sel_hi:[1,0] neg_lo:[0,1] neg_hi:[0,1]
	v_pk_add_f32 v[108:109], v[124:125], v[228:229] op_sel_hi:[1,0] neg_lo:[0,1] neg_hi:[0,1]
	v_pk_add_f32 v[110:111], v[126:127], v[228:229] op_sel_hi:[1,0] neg_lo:[0,1] neg_hi:[0,1]
	v_max_f32_e32 v97, v80, v81
	v_pk_add_f32 v[14:15], v[128:129], v[228:229] op_sel_hi:[1,0] neg_lo:[0,1] neg_hi:[0,1]
	v_max3_f32 v112, v98, v99, v100
	v_pk_add_f32 v[82:83], v[130:131], v[228:229] op_sel_hi:[1,0] neg_lo:[0,1] neg_hi:[0,1]
	v_max3_f32 v97, v97, v101, v102
	v_pk_add_f32 v[84:85], v[132:133], v[228:229] op_sel_hi:[1,0] neg_lo:[0,1] neg_hi:[0,1]
	v_max3_f32 v112, v112, v103, v104
	s_addc_u32 s23, s31, 0
	v_pk_add_f32 v[86:87], v[134:135], v[228:229] op_sel_hi:[1,0] neg_lo:[0,1] neg_hi:[0,1]
	v_max3_f32 v97, v97, v105, v106
	s_add_i32 s24, s29, s57
	v_pk_add_f32 v[88:89], v[136:137], v[228:229] op_sel_hi:[1,0] neg_lo:[0,1] neg_hi:[0,1]
	v_max3_f32 v112, v112, v107, v108
	s_add_u32 s62, s18, s10
	v_pk_add_f32 v[90:91], v[138:139], v[228:229] op_sel_hi:[1,0] neg_lo:[0,1] neg_hi:[0,1]
	v_max3_f32 v97, v97, v109, v110
	s_addc_u32 s63, s19, s11
	v_pk_add_f32 v[92:93], v[140:141], v[228:229] op_sel_hi:[1,0] neg_lo:[0,1] neg_hi:[0,1]
	v_max3_f32 v112, v112, v111, v14
	v_pk_add_f32 v[94:95], v[142:143], v[228:229] op_sel_hi:[1,0] neg_lo:[0,1] neg_hi:[0,1]
	v_max3_f32 v97, v97, v15, v82
	v_max3_f32 v112, v112, v83, v84
	v_max3_f32 v97, v97, v85, v86
	v_max3_f32 v112, v112, v87, v88
	v_max3_f32 v97, v97, v89, v90
	v_max3_f32 v112, v112, v91, v92
	v_max3_f32 v97, v97, v94, v95
	s_mov_b32 s25, m0
	s_mov_b32 m0, s24
	s_nop 0
	global_load_lds_dwordx4 v241, s[22:23]
	s_mov_b32 m0, s25
	s_add_u32 s22, s62, 0x40000
	v_add_f32_e32 v116, v224, v96
	v_max3_f32 v96, v97, v93, v112
	s_addc_u32 s23, s63, 0
	s_add_i32 s24, s28, s58
	v_mov_b32_e32 v97, v96
	s_add_u32 s64, s20, s10
	s_nop 0
	v_permlane32_swap_b32_e32 v96, v97
	s_addc_u32 s65, s21, s11
	s_mov_b32 s25, m0
	s_mov_b32 m0, s24
	s_nop 0
	global_load_lds_dwordx4 v242, s[22:23]
	s_mov_b32 m0, s25
	s_add_u32 s22, s64, 0x40000
	v_max_f32_e32 v96, v96, v97
	s_addc_u32 s23, s65, 0
	s_add_i32 s24, s28, s59
	s_mov_b32 s25, m0
	s_mov_b32 m0, s24
	s_nop 0
	global_load_lds_dwordx4 v242, s[22:23]
	s_mov_b32 m0, s25
	v_cmp_lt_f32_e32 vcc, s35, v96
	s_cmp_lg_u64 vcc, 0
	s_cselect_b64 s[22:23], -1, 0
	s_cbranch_vccnz .LBB0_1612

.LBB0_1607:
	s_add_i32 s22, s28, 0x2000
	s_cmpk_lg_i32 s28, 0x4000
	s_cselect_b32 s61, s22, 0
	v_add_f32_e32 v15, v116, v14
	v_add_u32_e32 v14, s29, v244
	ds_read_b64_tr_b16 v[196:197], v14 offset:24576
	ds_read_b64_tr_b16 v[198:199], v14 offset:25088
	v_add_f32_e32 v132, v87, v88
	v_cvt_pk_bf16_f32 v156, v96, v97
	v_cvt_pk_bf16_f32 v157, v98, v99
	v_mfma_f32_32x32x16_bf16 v[112:127], v[112:115], v[172:175], 0
	ds_read_b64_tr_b16 v[192:193], v14 offset:28672
	ds_read_b64_tr_b16 v[194:195], v14 offset:29184
	v_add_f32_e32 v96, v89, v132
	v_cvt_pk_bf16_f32 v158, v100, v101
	v_cvt_pk_bf16_f32 v159, v102, v103
	v_mfma_f32_32x32x16_bf16 v[128:143], v[128:131], v[172:175], 0
	ds_read_b64_tr_b16 v[188:189], v14 offset:25600
	ds_read_b64_tr_b16 v[190:191], v14 offset:26112
	v_add_f32_e32 v96, v90, v96
	v_cvt_pk_bf16_f32 v152, v104, v105
	v_cvt_pk_bf16_f32 v153, v106, v107
	v_mfma_f32_32x32x16_bf16 v[112:127], v[184:187], v[168:171], v[112:127]
	ds_read_b64_tr_b16 v[184:185], v14 offset:29696
	ds_read_b64_tr_b16 v[186:187], v14 offset:30208
	v_add_f32_e32 v96, v91, v96
	v_cvt_pk_bf16_f32 v154, v108, v109
	v_cvt_pk_bf16_f32 v155, v110, v111
	v_mfma_f32_32x32x16_bf16 v[128:143], v[176:179], v[168:171], v[128:143]
	ds_read_b64_tr_b16 v[176:177], v14 offset:26624
	ds_read_b64_tr_b16 v[178:179], v14 offset:27136
	v_add_f32_e32 v96, v92, v96
	v_cvt_pk_bf16_f32 v148, v80, v81
	v_cvt_pk_bf16_f32 v149, v82, v83
	v_mfma_f32_32x32x16_bf16 v[112:127], v[180:183], v[164:167], v[112:127]
	ds_read_b64_tr_b16 v[212:213], v14 offset:30720
	ds_read_b64_tr_b16 v[214:215], v14 offset:31232
	v_add_f32_e32 v80, v93, v96
	v_cvt_pk_bf16_f32 v150, v84, v85
	v_cvt_pk_bf16_f32 v151, v86, v87
	v_mfma_f32_32x32x16_bf16 v[128:143], v[6:9], v[164:167], v[128:143]
	ds_read_b64_tr_b16 v[208:209], v14 offset:27648
	ds_read_b64_tr_b16 v[210:211], v14 offset:28160
	v_add_f32_e32 v80, v94, v80
	v_cvt_pk_bf16_f32 v144, v88, v89
	v_cvt_pk_bf16_f32 v145, v90, v91
	v_mfma_f32_32x32x16_bf16 v[112:127], v[10:13], v[160:163], v[112:127]
	ds_read_b64_tr_b16 v[6:7], v14 offset:31744
	ds_read_b64_tr_b16 v[8:9], v14 offset:32256
	v_add_f32_e32 v10, v95, v80
	v_cvt_pk_bf16_f32 v146, v92, v93
	v_cvt_pk_bf16_f32 v147, v94, v95
	v_mfma_f32_32x32x16_bf16 v[128:143], v[2:5], v[160:163], v[128:143]
	s_add_u32 s22, s30, 0xa0000
	s_addc_u32 s23, s31, 0
	s_mov_b32 s25, m0
	s_add_i32 s24, s28, s57
	s_mov_b32 m0, s24
	v_add_f32_e64 v4, v112, -v228
	global_load_lds_dwordx4 v241, s[22:23]
	s_mov_b32 m0, s25
	v_add_f32_e64 v5, v113, -v228
	v_pk_add_f32 v[98:99], v[114:115], v[228:229] op_sel_hi:[1,0] neg_lo:[0,1] neg_hi:[0,1]
	v_pk_add_f32 v[100:101], v[116:117], v[228:229] op_sel_hi:[1,0] neg_lo:[0,1] neg_hi:[0,1]
	v_pk_add_f32 v[102:103], v[118:119], v[228:229] op_sel_hi:[1,0] neg_lo:[0,1] neg_hi:[0,1]
	v_pk_add_f32 v[104:105], v[120:121], v[228:229] op_sel_hi:[1,0] neg_lo:[0,1] neg_hi:[0,1]
	v_pk_add_f32 v[106:107], v[122:123], v[228:229] op_sel_hi:[1,0] neg_lo:[0,1] neg_hi:[0,1]
	v_pk_add_f32 v[108:109], v[124:125], v[228:229] op_sel_hi:[1,0] neg_lo:[0,1] neg_hi:[0,1]
	v_pk_add_f32 v[110:111], v[126:127], v[228:229] op_sel_hi:[1,0] neg_lo:[0,1] neg_hi:[0,1]
	v_max_f32_e32 v11, v4, v5
	v_pk_add_f32 v[2:3], v[128:129], v[228:229] op_sel_hi:[1,0] neg_lo:[0,1] neg_hi:[0,1]
	v_max3_f32 v12, v98, v99, v100
	v_pk_add_f32 v[82:83], v[130:131], v[228:229] op_sel_hi:[1,0] neg_lo:[0,1] neg_hi:[0,1]
	v_max3_f32 v11, v11, v101, v102
	v_pk_add_f32 v[84:85], v[132:133], v[228:229] op_sel_hi:[1,0] neg_lo:[0,1] neg_hi:[0,1]
	v_max3_f32 v12, v12, v103, v104
	v_pk_add_f32 v[86:87], v[134:135], v[228:229] op_sel_hi:[1,0] neg_lo:[0,1] neg_hi:[0,1]
	v_max3_f32 v11, v11, v105, v106
	v_pk_add_f32 v[88:89], v[136:137], v[228:229] op_sel_hi:[1,0] neg_lo:[0,1] neg_hi:[0,1]
	v_max3_f32 v12, v12, v107, v108
	v_pk_add_f32 v[90:91], v[138:139], v[228:229] op_sel_hi:[1,0] neg_lo:[0,1] neg_hi:[0,1]
	v_max3_f32 v11, v11, v109, v110
	v_pk_add_f32 v[92:93], v[140:141], v[228:229] op_sel_hi:[1,0] neg_lo:[0,1] neg_hi:[0,1]
	v_max3_f32 v12, v12, v111, v2
	v_pk_add_f32 v[94:95], v[142:143], v[228:229] op_sel_hi:[1,0] neg_lo:[0,1] neg_hi:[0,1]
	v_max3_f32 v11, v11, v3, v82
	v_max3_f32 v12, v12, v83, v84
	v_max3_f32 v11, v11, v85, v86
	v_max3_f32 v12, v12, v87, v88
	v_max3_f32 v11, v11, v89, v90
	v_max3_f32 v12, v12, v91, v92
	v_max3_f32 v11, v11, v94, v95
	v_max3_f32 v11, v11, v93, v12
	v_mov_b32_e32 v12, v11
	s_add_u32 s22, s62, 0x60000
	s_nop 0
	v_permlane32_swap_b32_e32 v11, v12
	s_addc_u32 s23, s63, 0
	s_add_i32 s24, s61, s58
	s_mov_b32 s25, m0
	s_mov_b32 m0, s24
	s_nop 0
	global_load_lds_dwordx4 v242, s[22:23]
	s_mov_b32 m0, s25
	s_add_u32 s22, s64, 0x60000
	v_max_f32_e32 v11, v11, v12
	s_addc_u32 s23, s65, 0
	s_add_i32 s24, s61, s59
	s_mov_b32 s25, m0
	s_mov_b32 m0, s24
	s_nop 0
	global_load_lds_dwordx4 v242, s[22:23]
	s_mov_b32 m0, s25
	v_cmp_lt_f32_e32 vcc, s35, v11
	s_cmp_lg_u64 vcc, 0
	v_add_f32_e32 v10, v15, v10
	s_cselect_b64 s[22:23], -1, 0
	s_cbranch_vccnz .LBB0_1615
